# MLA loop: row-max tree split by key half (first half starts right behind its last MFMA), long s_nop removed
# baseline (speedup 1.0000x reference)
; #define MFMA(a, b, c) __builtin_amdgcn_mfma_f32_32x32x16_bf16((a), (b), (c), 0, 0, 0)
; DI float xhalf_max(float x) { const auto rr = __builtin_amdgcn_permlane32_swap(__float_as_uint(x), __float_as_uint(x), false, false); return fmaxf(__uint_as_float(rr[0]), __uint_as_float(rr[1])); }
; template <int DQK, int DV, bool BAND> ...
;     ...
;     if constexpr (DQK < 128) {
;       f32x16 p0, p1;
; #pragma unroll
;       for (int r = 0; r < 16; ++r) { p0[r] = 0.f; p1[r] = 0.f; }
;       __builtin_amdgcn_s_setprio(1);
; #pragma unroll
;       for (int d0 = 0; d0 < ND0; ++d0) {
;         const bf16x8 k0f = *(const bf16x8*)&Ks[r32 * KLD + d0 * 16 + hi * 8];
;         const bf16x8 k1f = *(const bf16x8*)&Ks[(32 + r32) * KLD + d0 * 16 + hi * 8];
;         p0 = MFMA(k0f, qf[d0], p0); p1 = MFMA(k1f, qf[d0], p1);
;       }
;       __builtin_amdgcn_s_setprio(0);
;       float mx = fmaxf(p0[0], p1[0]);
; #pragma unroll
;       for (int r = 1; r < 16; ++r) mx = fmaxf(mx, fmaxf(p0[r], p1[r]));
;       mx = xhalf_max(mx);
;       if (__builtin_amdgcn_ballot_w64(mx > m_run + 8.f) != 0ull) {
;         const float m_new = fmaxf(m_run, mx); const float m_use = (m_new == -INFINITY) ? 0.f : m_new;
;         const float alpha = __builtin_amdgcn_exp2f(m_run - m_use);
;         l_run *= alpha; m_run = m_new;
;         if (hi == 0) sc[r32] = alpha;
;         __builtin_amdgcn_fence(__ATOMIC_RELEASE, "wavefront");
;         __builtin_amdgcn_wave_barrier();
; #pragma unroll
;         for (int g4 = 0; g4 < 4; ++g4) { const f32x4 a4 = *(const f32x4*)&sc[8 * g4 + 4 * hi];
; #pragma unroll
;           for (int cb = 0; cb < NCB; ++cb)
; #pragma unroll
;             for (int j = 0; j < 4; ++j) o[cb][4 * g4 + j] *= a4[j]; }
;         __builtin_amdgcn_wave_barrier();
;       }
;       const float m_ref = (m_run == -INFINITY) ? 0.f : m_run;
.LBB1_320:
	ds_read_b128 v[208:211], v132
	ds_read_b128 v[212:215], v132 offset:6656
	ds_read_b128 v[216:219], v132 offset:32
	ds_read_b128 v[220:223], v132 offset:6688
	ds_read_b128 v[224:227], v132 offset:64
	ds_read_b128 v[228:231], v132 offset:6720
	ds_read_b128 v[232:235], v132 offset:96
	ds_read_b128 v[236:239], v132 offset:6752
	ds_read_b128 v[240:243], v132 offset:128
	ds_read_b128 v[244:247], v132 offset:6784
	ds_read_b128 v[248:251], v132 offset:160
	ds_read_b128 v[134:137], v132 offset:6816
	s_waitcnt lgkmcnt(11)
	v_mfma_f32_32x32x16_bf16 v[34:49], v[208:211], v[66:69], v[150:165]
	s_waitcnt lgkmcnt(10)
	v_mfma_f32_32x32x16_bf16 v[50:65], v[212:215], v[66:69], v[150:165]
	s_waitcnt lgkmcnt(9)
	v_mfma_f32_32x32x16_bf16 v[34:49], v[216:219], v[70:73], v[34:49]
	s_waitcnt lgkmcnt(8)
	v_mfma_f32_32x32x16_bf16 v[50:65], v[220:223], v[70:73], v[50:65]
	s_waitcnt lgkmcnt(7)
	v_mfma_f32_32x32x16_bf16 v[34:49], v[224:227], v[74:77], v[34:49]
	s_waitcnt lgkmcnt(6)
	v_mfma_f32_32x32x16_bf16 v[50:65], v[228:231], v[74:77], v[50:65]
	s_waitcnt lgkmcnt(5)
	v_mfma_f32_32x32x16_bf16 v[34:49], v[232:235], v[78:81], v[34:49]
	s_waitcnt lgkmcnt(4)
	v_mfma_f32_32x32x16_bf16 v[50:65], v[236:239], v[78:81], v[50:65]
	s_waitcnt lgkmcnt(3)
	v_mfma_f32_32x32x16_bf16 v[34:49], v[240:243], v[82:85], v[34:49]
	s_waitcnt lgkmcnt(2)
	v_mfma_f32_32x32x16_bf16 v[50:65], v[244:247], v[82:85], v[50:65]
	s_waitcnt lgkmcnt(1)
	v_mfma_f32_32x32x16_bf16 v[34:49], v[248:251], v[86:89], v[34:49]
	s_waitcnt lgkmcnt(0)
	v_mfma_f32_32x32x16_bf16 v[50:65], v[134:137], v[86:89], v[50:65]
	ds_read2_b64 v[208:211], v166 offset0:128 offset1:130
	ds_read2_b64 v[212:215], v167 offset0:160 offset1:162
	ds_read2_b64 v[216:219], v166 offset0:136 offset1:138
	ds_read2_b64 v[220:223], v167 offset0:168 offset1:170
	ds_read2_b64 v[224:227], v166 offset0:132 offset1:134
	ds_read2_b64 v[228:231], v167 offset0:164 offset1:166
	ds_read2_b64 v[232:235], v166 offset0:140 offset1:142
	ds_read2_b64 v[236:239], v167 offset0:172 offset1:174
	s_nop 1
	v_max3_f32 v0, v34, v35, v36
	v_max3_f32 v0, v0, v37, v38
	v_max3_f32 v0, v0, v39, v40
	v_max3_f32 v0, v0, v41, v42
	v_max3_f32 v0, v0, v43, v44
	v_max3_f32 v0, v0, v45, v46
	v_max3_f32 v0, v0, v47, v48
	v_max_f32_e32 v0, v0, v49
	v_max3_f32 v134, v50, v51, v52
	v_max3_f32 v134, v134, v53, v54
	v_max3_f32 v134, v134, v55, v56
	v_max3_f32 v134, v134, v57, v58
	v_max3_f32 v134, v134, v59, v60
	v_max3_f32 v134, v134, v61, v62
	v_max3_f32 v134, v134, v63, v64
	v_max_f32_e32 v134, v134, v65
	v_max_f32_e32 v0, v0, v134
	v_mov_b32_e32 v134, v0
	s_nop 1
	v_permlane32_swap_b32_e32 v0, v134
	v_max_f32_e32 v0, v0, v134
	v_sub_f32_e32 v0, v0, v150
	v_add_f32_e32 v134, 0x41000000, v133
	v_cmp_gt_f32_e32 vcc, v0, v134
	s_cbranch_vccz .LBB1_324
	v_max_f32_e32 v0, v0, v0
	v_max_f32_e32 v134, v133, v133
	v_max_f32_e32 v0, v134, v0
	v_cmp_neq_f32_e32 vcc, s7, v0
	s_nop 1
	v_cndmask_b32_e32 v134, 0, v0, vcc
	v_sub_f32_e32 v133, v133, v134
	v_exp_f32_e32 v133, v133
	v_add_f32_e32 v168, v150, v134
	s_and_saveexec_b64 s[22:23], s[36:37]
	ds_write_b32 v124, v133 offset:34816
	s_or_b64 exec, exec, s[22:23]
	s_waitcnt lgkmcnt(0)
	ds_read_b128 v[136:139], v120 offset:34816
	ds_read_b128 v[140:143], v120 offset:34848
	ds_read_b128 v[144:147], v120 offset:34880
	ds_read_b128 v[240:243], v120 offset:34912
	v_mul_f32_e32 v126, v126, v133
	v_sub_f32_e32 v34, v34, v168
	v_sub_f32_e32 v35, v35, v168
	v_sub_f32_e32 v36, v36, v168
	v_sub_f32_e32 v37, v37, v168
	v_sub_f32_e32 v38, v38, v168
	v_sub_f32_e32 v39, v39, v168
	v_sub_f32_e32 v40, v40, v168
	v_sub_f32_e32 v41, v41, v168
	v_sub_f32_e32 v42, v42, v168
	v_sub_f32_e32 v43, v43, v168
	v_sub_f32_e32 v44, v44, v168
	v_sub_f32_e32 v45, v45, v168
	v_sub_f32_e32 v46, v46, v168
	v_sub_f32_e32 v47, v47, v168
	v_sub_f32_e32 v48, v48, v168
	v_sub_f32_e32 v49, v49, v168
	v_sub_f32_e32 v50, v50, v168
	v_sub_f32_e32 v51, v51, v168
	v_sub_f32_e32 v52, v52, v168
	v_sub_f32_e32 v53, v53, v168
	v_sub_f32_e32 v54, v54, v168
	v_sub_f32_e32 v55, v55, v168
	v_sub_f32_e32 v56, v56, v168
	v_sub_f32_e32 v57, v57, v168
	v_sub_f32_e32 v58, v58, v168
	v_sub_f32_e32 v59, v59, v168
	v_sub_f32_e32 v60, v60, v168
	v_sub_f32_e32 v61, v61, v168
	v_sub_f32_e32 v62, v62, v168
	v_sub_f32_e32 v63, v63, v168
	v_sub_f32_e32 v64, v64, v168
	v_sub_f32_e32 v65, v65, v168
	v_sub_f32_e32 v150, 0, v134
	v_mov_b32_e32 v151, v150
	v_mov_b32_e32 v152, v150
	v_mov_b32_e32 v153, v150
	v_mov_b32_e32 v154, v150
	v_mov_b32_e32 v155, v150
	v_mov_b32_e32 v156, v150
	v_mov_b32_e32 v157, v150
	v_mov_b32_e32 v158, v150
	v_mov_b32_e32 v159, v150
	v_mov_b32_e32 v160, v150
	v_mov_b32_e32 v161, v150
	v_mov_b32_e32 v162, v150
	v_mov_b32_e32 v163, v150
	v_mov_b32_e32 v164, v150
	v_mov_b32_e32 v165, v150
	s_waitcnt lgkmcnt(0)
	v_pk_mul_f32 v[2:3], v[2:3], v[136:137]
	v_pk_mul_f32 v[4:5], v[4:5], v[138:139]
	v_pk_mul_f32 v[6:7], v[6:7], v[140:141]
	v_pk_mul_f32 v[8:9], v[8:9], v[142:143]
	v_pk_mul_f32 v[10:11], v[10:11], v[144:145]
	v_pk_mul_f32 v[12:13], v[12:13], v[146:147]
	v_pk_mul_f32 v[14:15], v[14:15], v[240:241]
	v_pk_mul_f32 v[16:17], v[16:17], v[242:243]
	v_pk_mul_f32 v[18:19], v[18:19], v[136:137]
	v_pk_mul_f32 v[20:21], v[20:21], v[138:139]
	v_pk_mul_f32 v[22:23], v[22:23], v[140:141]
	v_pk_mul_f32 v[24:25], v[24:25], v[142:143]
	v_pk_mul_f32 v[26:27], v[26:27], v[144:145]
	v_pk_mul_f32 v[28:29], v[28:29], v[146:147]
	v_pk_mul_f32 v[30:31], v[30:31], v[240:241]
	v_pk_mul_f32 v[32:33], v[32:33], v[242:243]
	s_branch .LBB1_325
